# lora epilogue sigmoid: v_rcp_f32 instead of the IEEE f32 divide chain (same as the w13 epilogue)
# baseline (speedup 1.0000x reference)
.LBB0_705:
	ds_read2_b32 v[2:3], v6 offset1:65
	s_waitcnt lgkmcnt(0)
	v_add_f32_e32 v2, v0, v2
	v_mul_f32_e32 v2, 0xbfb8aa3b, v2
	v_exp_f32_e32 v2, v2
	s_nop 0
	v_add_f32_e32 v2, 1.0, v2
	s_nop 0
	v_rcp_f32_e32 v2, v2
	v_lshl_add_u64 v[8:9], v[4:5], 0, s[0:1]
	global_store_dword v[8:9], v2, off offset:-4096
	v_add_f32_e32 v2, v0, v3
	v_mul_f32_e32 v2, 0xbfb8aa3b, v2
	v_exp_f32_e32 v2, v2
	s_add_u32 s0, s0, 0x4000
	s_addc_u32 s1, s1, 0
	s_cmp_eq_u32 s0, 0x40000
	v_add_f32_e32 v2, 1.0, v2
	s_nop 0
	v_rcp_f32_e32 v2, v2
	s_nop 0
	global_store_dword v[8:9], v2, off
	ds_read2_b32 v[2:3], v6 offset0:130 offset1:195
	v_add_u32_e32 v6, 0x410, v6
	s_waitcnt lgkmcnt(0)
	v_add_f32_e32 v2, v0, v2
	v_mul_f32_e32 v2, 0xbfb8aa3b, v2
	v_exp_f32_e32 v2, v2
	s_nop 0
	v_add_f32_e32 v2, 1.0, v2
	s_nop 0
	v_add_co_u32_e32 v10, vcc, s22, v8
	v_rcp_f32_e32 v2, v2
	s_nop 0
	v_addc_co_u32_e32 v11, vcc, 0, v9, vcc
	global_store_dword v[10:11], v2, off
	v_add_f32_e32 v2, v0, v3
	v_mul_f32_e32 v2, 0xbfb8aa3b, v2
	v_exp_f32_e32 v2, v2
	s_nop 0
	v_add_f32_e32 v2, 1.0, v2
	s_nop 0
	v_rcp_f32_e32 v7, v2
	v_add_co_u32_e32 v2, vcc, 0x2000, v8
	s_nop 1
	v_addc_co_u32_e32 v3, vcc, 0, v9, vcc
	global_store_dword v[2:3], v7, off
	s_cbranch_scc0 .LBB0_705
